# FF2 K-loop: LDS-DMA loads use scalar base + 32-bit lane offset instead of sixteen 64-bit VALU address adds per iteration
# speedup vs baseline: 1.0115x; 1.0018x over previous
; #define PG8_STAGE(bufoff, gbase, voff) do { _Pragma("unroll") for (int _i = 0; _i < 2; ++_i) \
;         __builtin_amdgcn_global_load_lds((const unsigned*)((const char*)(gbase) + (voff)[_i]), (LAS unsigned*)(lds + (bufoff) + ldsw + _i * 8192), 16, 0, 0); } while (0)
; #define PG8_LDA(dst, b, h) do { _Pragma("unroll") for (int m = 0; m < 4; ++m) _Pragma("unroll") for (int k = 0; k < 2; ++k) dst[m][k] = *(const LAS bf16x8*)(lds + PG8_SA(b, h) + aoff + m * 2048 + k * 1024); } while (0)
; #define PG8_LDB(dst, b, h) do { _Pragma("unroll") for (int n = 0; n < 2; ++n) _Pragma("unroll") for (int k = 0; k < 2; ++k) dst[n][k] = *(const LAS bf16x8*)(lds + PG8_SB(b, h) + boff + n * 2048 + k * 1024); } while (0)
; #define PG8_MMA(ai, bj, At, Bt) do { __builtin_amdgcn_s_setprio(1); _Pragma("unroll") for (int m = 0; m < 4; ++m) _Pragma("unroll") for (int n = 0; n < 2; ++n) _Pragma("unroll") for (int k = 0; k < 2; ++k) \
;         acc[ai][bj][m][n] = __builtin_amdgcn_mfma_f32_16x16x32_bf16(Bt[n][k], At[m][k], acc[ai][bj][m][n], 0, 0, 0); __builtin_amdgcn_s_setprio(0); } while (0)
; #define PG8_WAIT_V(n) asm volatile("s_waitcnt vmcnt(" #n ")" ::: "memory")
; #define PG8_WAIT_L(n) asm volatile("s_waitcnt lgkmcnt(" #n ")" ::: "memory")
; #define PG8_BAR __builtin_amdgcn_s_barrier()
; #define PG8_SCHED __builtin_amdgcn_sched_barrier(0)
; template <class Epi, class Sched>
; __device__ __forceinline__ void gemm_phase(LAS unsigned char* lds, const Gemm g, const Sched& S, const Epi& E) {
;     ...
;             PG8_LDB(B0, 0, 0); PG8_SCHED; PG8_LDA(At, 0, 0); PG8_STAGE(PG8_SA(1, 1), a1 + hstep, voffA);
;             PG8_WAIT_L(8); PG8_BAR; PG8_WAIT_L(0); PG8_MMA(0, 0, At, B0); PG8_BAR; PG8_SCHED;
;             PG8_LDB(B1, 0, 1); PG8_STAGE(PG8_SB(0, 0), b2, voffB);
;             PG8_BAR; PG8_WAIT_L(0); PG8_MMA(0, 1, At, B1); PG8_BAR;
;             PG8_LDA(At, 0, 1); PG8_STAGE(PG8_SA(0, 0), a2, voffA);
;             PG8_BAR; PG8_WAIT_L(0); PG8_MMA(1, 0, At, B0); PG8_BAR; PG8_SCHED;
;             PG8_STAGE(PG8_SB(0, 1), b2 + hstep, voffB);
;             PG8_WAIT_V(6); PG8_BAR; PG8_MMA(1, 1, At, B1); PG8_BAR;
.LBB0_1343:
	s_nop 0
	v_add_u32_e32 v136, s42, v139
	ds_read_b128 v[142:145], v136
	ds_read_b128 v[146:149], v136 offset:1024
	ds_read_b128 v[150:153], v136 offset:2048
	ds_read_b128 v[154:157], v136 offset:3072
	s_add_u32 s18, s16, 0x100
	s_addc_u32 s19, s17, 0
	s_cmpk_eq_i32 s40, 0x7c
	s_cselect_b32 s23, s3, s19
	s_cselect_b32 s22, s7, s18
	s_cselect_b32 s21, s5, s39
	s_cselect_b32 s20, s37, s38
	s_add_i32 m0, s13, 0xc000
	ds_read_b128 v[158:161], v141
	ds_read_b128 v[162:165], v141 offset:1024
	ds_read_b128 v[166:169], v141 offset:2048
	ds_read_b128 v[170:173], v141 offset:3072
	ds_read_b128 v[174:177], v141 offset:4096
	ds_read_b128 v[178:181], v141 offset:5120
	ds_read_b128 v[182:185], v141 offset:6144
	ds_read_b128 v[186:189], v141 offset:7168
	global_load_lds_dwordx4 v132, s[16:17]
	s_add_i32 m0, s13, 0xe000
	s_nop 0
	global_load_lds_dwordx4 v134, s[16:17]
	s_waitcnt lgkmcnt(8)
	s_barrier
	s_waitcnt lgkmcnt(0)
	v_mfma_f32_16x16x32_bf16 v[126:129], v[142:145], v[158:161], v[126:129]
	v_mfma_f32_16x16x32_bf16 v[122:125], v[150:153], v[158:161], v[122:125]
	v_mfma_f32_16x16x32_bf16 v[110:113], v[142:145], v[166:169], v[110:113]
	v_mfma_f32_16x16x32_bf16 v[106:109], v[150:153], v[166:169], v[106:109]
	v_mfma_f32_16x16x32_bf16 v[94:97], v[142:145], v[174:177], v[94:97]
	v_mfma_f32_16x16x32_bf16 v[90:93], v[150:153], v[174:177], v[90:93]
	v_mfma_f32_16x16x32_bf16 v[78:81], v[142:145], v[182:185], v[78:81]
	v_mfma_f32_16x16x32_bf16 v[74:77], v[150:153], v[182:185], v[74:77]
	v_mfma_f32_16x16x32_bf16 v[126:129], v[146:149], v[162:165], v[126:129]
	v_mfma_f32_16x16x32_bf16 v[122:125], v[154:157], v[162:165], v[122:125]
	v_mfma_f32_16x16x32_bf16 v[110:113], v[146:149], v[170:173], v[110:113]
	v_mfma_f32_16x16x32_bf16 v[106:109], v[154:157], v[170:173], v[106:109]
	v_mfma_f32_16x16x32_bf16 v[94:97], v[146:149], v[178:181], v[94:97]
	v_mfma_f32_16x16x32_bf16 v[90:93], v[154:157], v[178:181], v[90:93]
	v_mfma_f32_16x16x32_bf16 v[78:81], v[146:149], v[186:189], v[78:81]
	v_mfma_f32_16x16x32_bf16 v[74:77], v[154:157], v[186:189], v[74:77]
	s_barrier
	s_add_i32 s41, 0, 0x14000
	v_add_u32_e32 v136, s41, v139
	s_add_i32 s16, s42, s28
	ds_read_b128 v[190:193], v136
	ds_read_b128 v[194:197], v136 offset:1024
	ds_read_b128 v[198:201], v136 offset:2048
	ds_read_b128 v[202:205], v136 offset:3072
	s_mov_b32 m0, s16
	s_nop 0
	global_load_lds_dwordx4 v0, s[20:21]
	s_add_i32 m0, s16, 0x2000
	s_nop 0
	global_load_lds_dwordx4 v130, s[20:21]
	s_barrier
	s_waitcnt lgkmcnt(0)
	v_mfma_f32_16x16x32_bf16 v[118:121], v[190:193], v[158:161], v[118:121]
	v_mfma_f32_16x16x32_bf16 v[114:117], v[198:201], v[158:161], v[114:117]
	v_mfma_f32_16x16x32_bf16 v[102:105], v[190:193], v[166:169], v[102:105]
	v_mfma_f32_16x16x32_bf16 v[98:101], v[198:201], v[166:169], v[98:101]
	v_mfma_f32_16x16x32_bf16 v[86:89], v[190:193], v[174:177], v[86:89]
	v_mfma_f32_16x16x32_bf16 v[82:85], v[198:201], v[174:177], v[82:85]
	v_mfma_f32_16x16x32_bf16 v[70:73], v[190:193], v[182:185], v[70:73]
	v_mfma_f32_16x16x32_bf16 v[66:69], v[198:201], v[182:185], v[66:69]
	v_mfma_f32_16x16x32_bf16 v[118:121], v[194:197], v[162:165], v[118:121]
	v_mfma_f32_16x16x32_bf16 v[114:117], v[202:205], v[162:165], v[114:117]
	v_mfma_f32_16x16x32_bf16 v[102:105], v[194:197], v[170:173], v[102:105]
	v_mfma_f32_16x16x32_bf16 v[98:101], v[202:205], v[170:173], v[98:101]
	v_mfma_f32_16x16x32_bf16 v[86:89], v[194:197], v[178:181], v[86:89]
	v_mfma_f32_16x16x32_bf16 v[82:85], v[202:205], v[178:181], v[82:85]
	v_mfma_f32_16x16x32_bf16 v[70:73], v[194:197], v[186:189], v[70:73]
	v_mfma_f32_16x16x32_bf16 v[66:69], v[202:205], v[186:189], v[66:69]
	s_mov_b32 m0, s13
	s_barrier
	ds_read_b128 v[158:161], v141 offset:16384
	ds_read_b128 v[162:165], v141 offset:17408
	ds_read_b128 v[166:169], v141 offset:18432
	ds_read_b128 v[170:173], v141 offset:19456
	ds_read_b128 v[174:177], v141 offset:20480
	ds_read_b128 v[178:181], v141 offset:21504
	ds_read_b128 v[182:185], v141 offset:22528
	ds_read_b128 v[186:189], v141 offset:23552
	global_load_lds_dwordx4 v0, s[22:23]
	s_mov_b32 m0, s15
	s_nop 0
	global_load_lds_dwordx4 v130, s[22:23]
	s_barrier
	s_waitcnt lgkmcnt(0)
	v_mfma_f32_16x16x32_bf16 v[62:65], v[142:145], v[158:161], v[62:65]
	v_mfma_f32_16x16x32_bf16 v[58:61], v[150:153], v[158:161], v[58:61]
	v_mfma_f32_16x16x32_bf16 v[46:49], v[142:145], v[166:169], v[46:49]
	v_mfma_f32_16x16x32_bf16 v[42:45], v[150:153], v[166:169], v[42:45]
	v_mfma_f32_16x16x32_bf16 v[30:33], v[142:145], v[174:177], v[30:33]
	v_mfma_f32_16x16x32_bf16 v[26:29], v[150:153], v[174:177], v[26:29]
	v_mfma_f32_16x16x32_bf16 v[14:17], v[142:145], v[182:185], v[14:17]
	v_mfma_f32_16x16x32_bf16 v[10:13], v[150:153], v[182:185], v[10:13]
	v_mfma_f32_16x16x32_bf16 v[62:65], v[146:149], v[162:165], v[62:65]
	v_mfma_f32_16x16x32_bf16 v[58:61], v[154:157], v[162:165], v[58:61]
	v_mfma_f32_16x16x32_bf16 v[46:49], v[146:149], v[170:173], v[46:49]
	v_mfma_f32_16x16x32_bf16 v[42:45], v[154:157], v[170:173], v[42:45]
	v_mfma_f32_16x16x32_bf16 v[30:33], v[146:149], v[178:181], v[30:33]
	v_mfma_f32_16x16x32_bf16 v[26:29], v[154:157], v[178:181], v[26:29]
	v_mfma_f32_16x16x32_bf16 v[14:17], v[146:149], v[186:189], v[14:17]
	v_mfma_f32_16x16x32_bf16 v[10:13], v[154:157], v[186:189], v[10:13]
	s_barrier
	s_add_u32 s16, s20, 0x200000
	s_addc_u32 s17, s21, 0
	s_add_i32 s41, s41, s28
	s_mov_b32 m0, s41
	s_nop 0
	global_load_lds_dwordx4 v0, s[16:17]
	s_add_i32 m0, s41, 0x2000
	s_nop 0
	global_load_lds_dwordx4 v130, s[16:17]
	s_waitcnt vmcnt(6)
	s_barrier
; #define PG8_STAGE(bufoff, gbase, voff) do { _Pragma("unroll") for (int _i = 0; _i < 2; ++_i) \
;         __builtin_amdgcn_global_load_lds((const unsigned*)((const char*)(gbase) + (voff)[_i]), (LAS unsigned*)(lds + (bufoff) + ldsw + _i * 8192), 16, 0, 0); } while (0)
; #define PG8_LDA(dst, b, h) do { _Pragma("unroll") for (int m = 0; m < 4; ++m) _Pragma("unroll") for (int k = 0; k < 2; ++k) dst[m][k] = *(const LAS bf16x8*)(lds + PG8_SA(b, h) + aoff + m * 2048 + k * 1024); } while (0)
; #define PG8_LDB(dst, b, h) do { _Pragma("unroll") for (int n = 0; n < 2; ++n) _Pragma("unroll") for (int k = 0; k < 2; ++k) dst[n][k] = *(const LAS bf16x8*)(lds + PG8_SB(b, h) + boff + n * 2048 + k * 1024); } while (0)
; #define PG8_MMA(ai, bj, At, Bt) do { __builtin_amdgcn_s_setprio(1); _Pragma("unroll") for (int m = 0; m < 4; ++m) _Pragma("unroll") for (int n = 0; n < 2; ++n) _Pragma("unroll") for (int k = 0; k < 2; ++k) \
;         acc[ai][bj][m][n] = __builtin_amdgcn_mfma_f32_16x16x32_bf16(Bt[n][k], At[m][k], acc[ai][bj][m][n], 0, 0, 0); __builtin_amdgcn_s_setprio(0); } while (0)
; #define PG8_WAIT_V(n) asm volatile("s_waitcnt vmcnt(" #n ")" ::: "memory")
; #define PG8_WAIT_L(n) asm volatile("s_waitcnt lgkmcnt(" #n ")" ::: "memory")
; #define PG8_BAR __builtin_amdgcn_s_barrier()
; #define PG8_SCHED __builtin_amdgcn_sched_barrier(0)
; template <class Epi, class Sched>
; __device__ __forceinline__ void gemm_phase(LAS unsigned char* lds, const Gemm g, const Sched& S, const Epi& E) {
;     ...
;             PG8_STAGE(PG8_SB(0, 1), b2 + hstep, voffB);
;             PG8_WAIT_V(6); PG8_BAR; PG8_MMA(1, 1, At, B1); PG8_BAR;
;             PG8_LDB(B0, 1, 0); PG8_SCHED; PG8_LDA(At, 1, 0); PG8_STAGE(PG8_SA(0, 1), a2 + hstep, voffA);
;             PG8_WAIT_L(8); PG8_BAR; PG8_WAIT_L(0); PG8_MMA(0, 0, At, B0); PG8_BAR; PG8_SCHED;
;             PG8_LDB(B1, 1, 1); PG8_STAGE(PG8_SB(1, 0), b3, voffB);
;             PG8_BAR; PG8_WAIT_L(0); PG8_MMA(0, 1, At, B1); PG8_BAR;
;             PG8_LDA(At, 1, 1); PG8_STAGE(PG8_SA(1, 0), a3, voffA);
;             PG8_BAR; PG8_WAIT_L(0); PG8_MMA(1, 0, At, B0); PG8_BAR; PG8_SCHED;
	v_mfma_f32_16x16x32_bf16 v[54:57], v[190:193], v[158:161], v[54:57]
	v_mfma_f32_16x16x32_bf16 v[50:53], v[198:201], v[158:161], v[50:53]
	v_mfma_f32_16x16x32_bf16 v[38:41], v[190:193], v[166:169], v[38:41]
	v_mfma_f32_16x16x32_bf16 v[34:37], v[198:201], v[166:169], v[34:37]
	v_mfma_f32_16x16x32_bf16 v[22:25], v[190:193], v[174:177], v[22:25]
	v_mfma_f32_16x16x32_bf16 v[18:21], v[198:201], v[174:177], v[18:21]
	v_mfma_f32_16x16x32_bf16 v[6:9], v[190:193], v[182:185], v[6:9]
	v_mfma_f32_16x16x32_bf16 v[2:5], v[198:201], v[182:185], v[2:5]
	v_mfma_f32_16x16x32_bf16 v[54:57], v[194:197], v[162:165], v[54:57]
	v_mfma_f32_16x16x32_bf16 v[50:53], v[202:205], v[162:165], v[50:53]
	v_mfma_f32_16x16x32_bf16 v[38:41], v[194:197], v[170:173], v[38:41]
	v_mfma_f32_16x16x32_bf16 v[34:37], v[202:205], v[170:173], v[34:37]
	v_mfma_f32_16x16x32_bf16 v[22:25], v[194:197], v[178:181], v[22:25]
	v_mfma_f32_16x16x32_bf16 v[18:21], v[202:205], v[178:181], v[18:21]
	v_mfma_f32_16x16x32_bf16 v[6:9], v[194:197], v[186:189], v[6:9]
	v_mfma_f32_16x16x32_bf16 v[2:5], v[202:205], v[186:189], v[2:5]
	s_add_i32 s41, 0, 0x18000
	v_add_u32_e32 v154, s41, v139
	s_barrier
	ds_read_b128 v[142:145], v154
	ds_read_b128 v[146:149], v154 offset:1024
	ds_read_b128 v[150:153], v154 offset:2048
	ds_read_b128 v[154:157], v154 offset:3072
	s_add_u32 s16, s22, 0x200000
	s_addc_u32 s17, s23, 0
	s_mov_b32 m0, s29
	ds_read_b128 v[158:161], v141 offset:32768
	ds_read_b128 v[162:165], v141 offset:33792
	ds_read_b128 v[166:169], v141 offset:34816
	ds_read_b128 v[170:173], v141 offset:35840
	ds_read_b128 v[174:177], v141 offset:36864
	ds_read_b128 v[178:181], v141 offset:37888
	ds_read_b128 v[182:185], v141 offset:38912
	ds_read_b128 v[186:189], v141 offset:39936
	global_load_lds_dwordx4 v0, s[16:17]
	s_mov_b32 m0, s30
	s_add_u32 s44, s22, 0x80
	s_addc_u32 s45, s23, 0
	global_load_lds_dwordx4 v130, s[16:17]
	s_waitcnt lgkmcnt(8)
	s_barrier
	s_waitcnt lgkmcnt(0)
	v_mfma_f32_16x16x32_bf16 v[126:129], v[142:145], v[158:161], v[126:129]
	v_mfma_f32_16x16x32_bf16 v[122:125], v[150:153], v[158:161], v[122:125]
	v_mfma_f32_16x16x32_bf16 v[110:113], v[142:145], v[166:169], v[110:113]
	v_mfma_f32_16x16x32_bf16 v[106:109], v[150:153], v[166:169], v[106:109]
	v_mfma_f32_16x16x32_bf16 v[94:97], v[142:145], v[174:177], v[94:97]
	v_mfma_f32_16x16x32_bf16 v[90:93], v[150:153], v[174:177], v[90:93]
	v_mfma_f32_16x16x32_bf16 v[78:81], v[142:145], v[182:185], v[78:81]
	v_mfma_f32_16x16x32_bf16 v[74:77], v[150:153], v[182:185], v[74:77]
	v_mfma_f32_16x16x32_bf16 v[126:129], v[146:149], v[162:165], v[126:129]
	v_mfma_f32_16x16x32_bf16 v[122:125], v[154:157], v[162:165], v[122:125]
	v_mfma_f32_16x16x32_bf16 v[110:113], v[146:149], v[170:173], v[110:113]
	v_mfma_f32_16x16x32_bf16 v[106:109], v[154:157], v[170:173], v[106:109]
	v_mfma_f32_16x16x32_bf16 v[94:97], v[146:149], v[178:181], v[94:97]
	v_mfma_f32_16x16x32_bf16 v[90:93], v[154:157], v[178:181], v[90:93]
	v_mfma_f32_16x16x32_bf16 v[78:81], v[146:149], v[186:189], v[78:81]
	v_mfma_f32_16x16x32_bf16 v[74:77], v[154:157], v[186:189], v[74:77]
	s_barrier
	s_add_i32 s22, 0, 0x1c000
	s_add_i32 s23, s41, s28
	v_add_u32_e32 v202, s22, v139
	s_add_u32 s16, s20, 0x80
	s_addc_u32 s17, s21, 0
	s_mov_b32 m0, s23
	ds_read_b128 v[190:193], v202
	ds_read_b128 v[194:197], v202 offset:1024
	ds_read_b128 v[198:201], v202 offset:2048
	ds_read_b128 v[202:205], v202 offset:3072
	global_load_lds_dwordx4 v0, s[16:17]
	s_add_i32 m0, s23, 0x2000
	s_nop 0
	global_load_lds_dwordx4 v130, s[16:17]
	s_barrier
	s_waitcnt lgkmcnt(0)
	v_mfma_f32_16x16x32_bf16 v[118:121], v[190:193], v[158:161], v[118:121]
	v_mfma_f32_16x16x32_bf16 v[114:117], v[198:201], v[158:161], v[114:117]
	v_mfma_f32_16x16x32_bf16 v[102:105], v[190:193], v[166:169], v[102:105]
	v_mfma_f32_16x16x32_bf16 v[98:101], v[198:201], v[166:169], v[98:101]
	v_mfma_f32_16x16x32_bf16 v[86:89], v[190:193], v[174:177], v[86:89]
	v_mfma_f32_16x16x32_bf16 v[82:85], v[198:201], v[174:177], v[82:85]
	v_mfma_f32_16x16x32_bf16 v[70:73], v[190:193], v[182:185], v[70:73]
	v_mfma_f32_16x16x32_bf16 v[66:69], v[198:201], v[182:185], v[66:69]
	v_mfma_f32_16x16x32_bf16 v[118:121], v[194:197], v[162:165], v[118:121]
	v_mfma_f32_16x16x32_bf16 v[114:117], v[202:205], v[162:165], v[114:117]
	v_mfma_f32_16x16x32_bf16 v[102:105], v[194:197], v[170:173], v[102:105]
	v_mfma_f32_16x16x32_bf16 v[98:101], v[202:205], v[170:173], v[98:101]
	v_mfma_f32_16x16x32_bf16 v[86:89], v[194:197], v[178:181], v[86:89]
	v_mfma_f32_16x16x32_bf16 v[82:85], v[202:205], v[178:181], v[82:85]
	v_mfma_f32_16x16x32_bf16 v[70:73], v[194:197], v[186:189], v[70:73]
	v_mfma_f32_16x16x32_bf16 v[66:69], v[202:205], v[186:189], v[66:69]
	s_mov_b32 m0, s34
	s_barrier
; #define PG8_STAGE(bufoff, gbase, voff) do { _Pragma("unroll") for (int _i = 0; _i < 2; ++_i) \
;         __builtin_amdgcn_global_load_lds((const unsigned*)((const char*)(gbase) + (voff)[_i]), (LAS unsigned*)(lds + (bufoff) + ldsw + _i * 8192), 16, 0, 0); } while (0)
; #define PG8_LDA(dst, b, h) do { _Pragma("unroll") for (int m = 0; m < 4; ++m) _Pragma("unroll") for (int k = 0; k < 2; ++k) dst[m][k] = *(const LAS bf16x8*)(lds + PG8_SA(b, h) + aoff + m * 2048 + k * 1024); } while (0)
; #define PG8_MMA(ai, bj, At, Bt) do { __builtin_amdgcn_s_setprio(1); _Pragma("unroll") for (int m = 0; m < 4; ++m) _Pragma("unroll") for (int n = 0; n < 2; ++n) _Pragma("unroll") for (int k = 0; k < 2; ++k) \
;         acc[ai][bj][m][n] = __builtin_amdgcn_mfma_f32_16x16x32_bf16(Bt[n][k], At[m][k], acc[ai][bj][m][n], 0, 0, 0); __builtin_amdgcn_s_setprio(0); } while (0)
; template <class Epi, class Sched>
; __device__ __forceinline__ void gemm_phase(LAS unsigned char* lds, const Gemm g, const Sched& S, const Epi& E) {
;     ...
;             PG8_LDA(At, 1, 1); PG8_STAGE(PG8_SA(1, 0), a3, voffA);
;             PG8_BAR; PG8_WAIT_L(0); PG8_MMA(1, 0, At, B0); PG8_BAR; PG8_SCHED;
;             PG8_STAGE(PG8_SB(1, 1), b3 + hstep, voffB);
;             PG8_WAIT_V(6); PG8_BAR; PG8_MMA(1, 1, At, B1); PG8_BAR;
;     __device__ __forceinline__ void operator()(const f32x4 (&acc)[2][2][4][2], const pg8::Unit& u, int wr, int wc, int fr, int fq) const {
;         const int row0 = u.pm * 256 + wr * 64 + fr; const int col0 = u.pn * 256 + wc * 32 + 4 * fq;
; #pragma unroll
;         for (int ai = 0; ai < 2; ++ai)
; #pragma unroll
;             for (int m = 0; m < 4; ++m) { const int row = row0 + ai * 128 + m * 16;
;                 const float* ip; float* op; int b;
;                 if (row < ML_ROWS) { b = row >> 11; ip = xi + (size_t)row * D; op = xo + (size_t)row * D; }
;                 else { b = 8; ip = ci + (size_t)(row - ML_ROWS) * D; op = co + (size_t)(row - ML_ROWS) * D; }
;                 const float* gp = mod + (size_t)b * 12288 + slot * 2048;
; #pragma unroll
;                 for (int bj = 0; bj < 2; ++bj)
; #pragma unroll
;                     for (int n = 0; n < 2; ++n) { const int c = col0 + bj * 128 + n * 16;
;                         const f32x4 r = *(const f32x4*)(ip + c), g = *(const f32x4*)(gp + c);
;                         *(f32x4*)(op + c) = r + g * acc[ai][bj][m][n]; } }
	ds_read_b128 v[158:161], v141 offset:49152
	ds_read_b128 v[162:165], v141 offset:50176
	ds_read_b128 v[166:169], v141 offset:51200
	ds_read_b128 v[170:173], v141 offset:52224
	ds_read_b128 v[174:177], v141 offset:53248
	ds_read_b128 v[178:181], v141 offset:54272
	ds_read_b128 v[182:185], v141 offset:55296
	ds_read_b128 v[186:189], v141 offset:56320
	global_load_lds_dwordx4 v0, s[44:45]
	s_mov_b32 m0, s35
	s_nop 0
	global_load_lds_dwordx4 v130, s[44:45]
	s_barrier
	s_waitcnt lgkmcnt(0)
	v_mfma_f32_16x16x32_bf16 v[62:65], v[142:145], v[158:161], v[62:65]
	v_mfma_f32_16x16x32_bf16 v[58:61], v[150:153], v[158:161], v[58:61]
	v_mfma_f32_16x16x32_bf16 v[46:49], v[142:145], v[166:169], v[46:49]
	v_mfma_f32_16x16x32_bf16 v[42:45], v[150:153], v[166:169], v[42:45]
	v_mfma_f32_16x16x32_bf16 v[30:33], v[142:145], v[174:177], v[30:33]
	v_mfma_f32_16x16x32_bf16 v[26:29], v[150:153], v[174:177], v[26:29]
	v_mfma_f32_16x16x32_bf16 v[14:17], v[142:145], v[182:185], v[14:17]
	v_mfma_f32_16x16x32_bf16 v[10:13], v[150:153], v[182:185], v[10:13]
	v_mfma_f32_16x16x32_bf16 v[62:65], v[146:149], v[162:165], v[62:65]
	v_mfma_f32_16x16x32_bf16 v[58:61], v[154:157], v[162:165], v[58:61]
	v_mfma_f32_16x16x32_bf16 v[46:49], v[146:149], v[170:173], v[46:49]
	v_mfma_f32_16x16x32_bf16 v[42:45], v[154:157], v[170:173], v[42:45]
	v_mfma_f32_16x16x32_bf16 v[30:33], v[146:149], v[178:181], v[30:33]
	v_mfma_f32_16x16x32_bf16 v[26:29], v[154:157], v[178:181], v[26:29]
	v_mfma_f32_16x16x32_bf16 v[14:17], v[146:149], v[186:189], v[14:17]
	v_mfma_f32_16x16x32_bf16 v[10:13], v[154:157], v[186:189], v[10:13]
	s_barrier
	s_add_u32 s16, s20, 0x200080
	s_addc_u32 s17, s21, 0
	s_add_i32 s20, s22, s28
	s_mov_b32 m0, s20
	s_nop 0
	global_load_lds_dwordx4 v0, s[16:17]
	s_add_i32 m0, s20, 0x2000
	s_nop 0
	global_load_lds_dwordx4 v130, s[16:17]
	s_waitcnt vmcnt(6)
	s_barrier
	v_mfma_f32_16x16x32_bf16 v[54:57], v[190:193], v[158:161], v[54:57]
	v_mfma_f32_16x16x32_bf16 v[50:53], v[198:201], v[158:161], v[50:53]
	v_mfma_f32_16x16x32_bf16 v[38:41], v[190:193], v[166:169], v[38:41]
	v_mfma_f32_16x16x32_bf16 v[34:37], v[198:201], v[166:169], v[34:37]
	v_mfma_f32_16x16x32_bf16 v[22:25], v[190:193], v[174:177], v[22:25]
	v_mfma_f32_16x16x32_bf16 v[18:21], v[198:201], v[174:177], v[18:21]
	v_mfma_f32_16x16x32_bf16 v[6:9], v[190:193], v[182:185], v[6:9]
	v_mfma_f32_16x16x32_bf16 v[2:5], v[198:201], v[182:185], v[2:5]
	v_mfma_f32_16x16x32_bf16 v[54:57], v[194:197], v[162:165], v[54:57]
	v_mfma_f32_16x16x32_bf16 v[50:53], v[202:205], v[162:165], v[50:53]
	v_mfma_f32_16x16x32_bf16 v[38:41], v[194:197], v[170:173], v[38:41]
	v_mfma_f32_16x16x32_bf16 v[34:37], v[202:205], v[170:173], v[34:37]
	v_mfma_f32_16x16x32_bf16 v[22:25], v[194:197], v[178:181], v[22:25]
	v_mfma_f32_16x16x32_bf16 v[18:21], v[202:205], v[178:181], v[18:21]
	v_mfma_f32_16x16x32_bf16 v[6:9], v[194:197], v[186:189], v[6:9]
	v_mfma_f32_16x16x32_bf16 v[2:5], v[202:205], v[186:189], v[2:5]
	s_add_i32 s40, s40, 2
	s_add_u32 s38, s38, 0x100
	s_addc_u32 s39, s39, 0
	s_cmpk_gt_u32 s40, 0x7d
	s_mov_b64 s[16:17], s[18:19]
	s_barrier
	s_cbranch_scc0 .LBB0_1343
	s_lshl_b32 s3, s14, 8
	s_add_i32 s3, s3, s31
	v_readlane_b32 s40, v251, 0
	v_readlane_b32 s41, v251, 1
	v_readlane_b32 s42, v251, 2
	v_readlane_b32 s43, v251, 3
	v_readlane_b32 s44, v251, 4
	v_readlane_b32 s45, v251, 5
	v_readlane_b32 s46, v251, 6
	v_readlane_b32 s47, v251, 7
	v_readlane_b32 s18, v254, 2
	v_readlane_b32 s19, v254, 3
	s_add_i32 s5, s3, 0xffffc000
	s_ashr_i32 s7, s3, 11
	s_cmpk_lt_i32 s3, 0x4000
	s_cselect_b32 s20, s42, s60
	s_cselect_b32 s21, s43, s61
	s_cselect_b32 s5, s3, s5
	s_cselect_b32 s7, s7, 8
	s_mul_i32 s7, s7, 0xc000
	s_add_u32 s18, s18, s7
	s_addc_u32 s19, s19, 0
	s_add_u32 s18, s18, 0xa000
	s_addc_u32 s19, s19, 0
	v_add_u32_e32 v136, s5, v138
	v_lshl_or_b32 v137, s12, 8, v140
	v_lshlrev_b32_e32 v137, 2, v137
	v_lshl_or_b32 v136, v136, 13, v137
	s_mov_b32 s12, s4
	s_mov_b32 s14, s6
	s_cmp_lg_u32 s36, 3
	s_cbranch_scc1 .Lsk_normal
	v_readlane_b32 s5, v253, 24
	s_cmpk_lg_u32 s46, 0x100
	s_cbranch_scc1 .Lsk_normal
	s_cmpk_lg_u32 s5, 0x240
	s_cbranch_scc1 .Lsk_normal
	s_and_b32 s7, s54, 3
	s_lshr_b32 s5, s54, 2
	s_lshr_b32 s3, s24, 6
	s_lshl_b32 s23, s5, 3
	s_add_i32 s23, s23, s3
	s_lshl_b32 s23, s23, 2
	v_readlane_b32 s38, v251, 10
	v_readlane_b32 s39, v251, 11
	s_add_u32 s38, s38, s23
	s_addc_u32 s39, s39, 0
	s_add_u32 s38, s38, 0x3700
	s_addc_u32 s39, s39, 0
	v_readlane_b32 s16, v251, 4
	v_readlane_b32 s17, v251, 5
	s_lshl_b32 s5, s5, 20
	s_add_u32 s16, s16, 0x24000000
	s_addc_u32 s17, s17, 0
	s_add_u32 s16, s16, s5
	s_addc_u32 s17, s17, 0
	v_add_u32_e32 v142, s31, v138
	v_lshlrev_b32_e32 v143, 2, v140
	v_lshl_or_b32 v142, v142, 10, v143
	global_load_dwordx4 v[146:149], v137, s[18:19]
	global_load_dwordx4 v[150:153], v137, s[18:19] offset:64
	global_load_dwordx4 v[154:157], v137, s[18:19] offset:512
	global_load_dwordx4 v[158:161], v137, s[18:19] offset:576
	s_cmp_eq_u32 s7, 1
	s_cbranch_scc1 .Lsk_v1
	s_cmp_eq_u32 s7, 2
	s_cbranch_scc1 .Lsk_v2
	s_cmp_eq_u32 s7, 3
	s_cbranch_scc1 .Lsk_v3
